# weight conversion moved from P0 into the P1 phase and co-scheduled with the pre-norm rows (waves 0-3 rows first, waves 4-7 conversion first)
# speedup vs baseline: 1.0572x; 1.0053x over previous
.LBB0_35:
	s_or_b64 exec, exec, s[2:3]
	s_load_dwordx16 s[4:19], s[0:1], 0x40
	s_lshl_b32 s0, s64, 3
	s_lshl_b32 s52, s90, 3
	s_waitcnt lgkmcnt(0)
	v_writelane_b32 v254, s4, 31
	s_nop 1
	v_writelane_b32 v254, s5, 32
	v_writelane_b32 v254, s6, 33
	v_writelane_b32 v254, s7, 34
	v_writelane_b32 v254, s8, 35
	v_writelane_b32 v254, s9, 36
	v_writelane_b32 v254, s10, 37
	v_writelane_b32 v254, s11, 38
	v_writelane_b32 v254, s12, 39
	v_writelane_b32 v254, s13, 40
	v_writelane_b32 v254, s14, 41
	v_writelane_b32 v254, s15, 42
	v_writelane_b32 v254, s16, 43
	v_writelane_b32 v254, s17, 44
	v_writelane_b32 v254, s18, 45
	v_writelane_b32 v254, s19, 46
	s_add_i32 s4, s60, s0
	s_add_u32 s2, s82, 0x1000000
	s_addc_u32 s3, s83, 0
	s_add_u32 s14, s82, 0x1500000
	s_addc_u32 s15, s83, 0
	s_add_u32 s12, s82, 0x1600000
	s_addc_u32 s13, s83, 0
	s_add_u32 s0, s82, 0x1700000
	s_addc_u32 s1, s83, 0
	v_writelane_b32 v254, s0, 27
	s_nop 1
	v_writelane_b32 v254, s1, 28
	s_add_u32 s0, s82, 0x1900000
	s_addc_u32 s1, s83, 0
	v_writelane_b32 v254, s0, 29
	s_add_u32 s84, s82, 0x2400000
	s_addc_u32 s85, s83, 0
	v_writelane_b32 v254, s1, 30
	s_mov_b32 s0, s4
	v_writelane_b32 v254, s0, 21
	s_cmpk_gt_i32 s4, 0x180f
	s_nop 0
	v_writelane_b32 v254, s1, 22
	s_mov_b32 s98, 0
	s_mov_b32 s99, s73
	s_branch .LBB0_226
.Lp01_bb36:
	v_lshrrev_b32_e32 v17, 5, v140
	s_movk_i32 s1, 0x84
	v_mov_b32_e32 v0, 0x108
	v_mad_u32_u24 v21, v17, s1, v0
	v_mov_b32_e32 v0, 0x210
	v_mad_u32_u24 v23, v17, s1, v0
	v_mov_b32_e32 v0, 0x318
	v_mad_u32_u24 v25, v17, s1, v0
	v_mov_b32_e32 v0, 0x420
	v_mad_u32_u24 v27, v17, s1, v0
	v_mov_b32_e32 v0, 0x528
	v_mad_u32_u24 v29, v17, s1, v0
	v_mov_b32_e32 v0, 0x630
	v_mad_u32_u24 v31, v17, s1, v0
	v_mov_b32_e32 v0, 0x738
	v_mad_u32_u24 v33, v17, s1, v0
	v_mov_b32_e32 v0, 0x840
	v_mad_u32_u24 v35, v17, s1, v0
	v_mov_b32_e32 v0, 0x948
	v_mad_u32_u24 v37, v17, s1, v0
	v_mov_b32_e32 v0, 0xa50
	v_mad_u32_u24 v39, v17, s1, v0
	v_mov_b32_e32 v0, 0xb58
	v_mad_u32_u24 v41, v17, s1, v0
	v_mov_b32_e32 v0, 0xc60
	v_mad_u32_u24 v43, v17, s1, v0
	v_mov_b32_e32 v0, 0xd68
	v_mad_u32_u24 v45, v17, s1, v0
	v_mov_b32_e32 v0, 0xe70
	v_mad_u32_u24 v47, v17, s1, v0
	v_mov_b32_e32 v0, 0xf78
	v_mad_u32_u24 v49, v17, s1, v0
	v_mov_b32_e32 v0, 0x1080
	v_mad_u32_u24 v51, v17, s1, v0
	v_mov_b32_e32 v0, 0x1188
	v_mad_u32_u24 v53, v17, s1, v0
	v_mov_b32_e32 v0, 0x1290
	v_mad_u32_u24 v55, v17, s1, v0
	v_mov_b32_e32 v0, 0x1398
	v_mad_u32_u24 v57, v17, s1, v0
	v_mov_b32_e32 v0, 0x14a0
	v_mad_u32_u24 v59, v17, s1, v0
	v_mov_b32_e32 v0, 0x15a8
	v_mad_u32_u24 v61, v17, s1, v0
	v_mov_b32_e32 v0, 0x16b0
	v_mad_u32_u24 v63, v17, s1, v0
	v_mov_b32_e32 v0, 0x17b8
	v_mad_u32_u24 v65, v17, s1, v0
	v_mov_b32_e32 v0, 0x18c0
	v_mad_u32_u24 v67, v17, s1, v0
	v_lshlrev_b32_e32 v0, 3, v140
	s_lshl_b32 s0, s60, 14
	v_lshrrev_b32_e32 v75, 3, v140
	v_and_b32_e32 v0, 56, v0
	s_add_i32 s0, s0, 0
	v_and_b32_e32 v16, 31, v141
	v_mul_u32_u24_e32 v4, 0x84, v0
	v_lshlrev_b32_e32 v5, 2, v75
	v_readlane_b32 s16, v254, 31
	v_lshl_add_u32 v18, v16, 2, s0
	v_add3_u32 v76, s0, v4, v5
	v_readlane_b32 s0, v254, 29
	v_readlane_b32 s17, v254, 32
	v_readlane_b32 s18, v254, 33
	v_readlane_b32 s19, v254, 34
	v_readlane_b32 s20, v254, 35
	v_readlane_b32 s21, v254, 36
	v_readlane_b32 s22, v254, 37
	v_readlane_b32 s23, v254, 38
	v_readlane_b32 s24, v254, 39
	v_readlane_b32 s25, v254, 40
	v_readlane_b32 s26, v254, 41
	v_readlane_b32 s27, v254, 42
	v_readlane_b32 s28, v254, 43
	v_readlane_b32 s29, v254, 44
	v_readlane_b32 s30, v254, 45
	v_readlane_b32 s31, v254, 46
	v_lshlrev_b32_e32 v0, 1, v0
	v_mov_b32_e32 v1, 0
	v_readlane_b32 s1, v254, 30
	s_cmp_lg_u64 s[18:19], 0
	v_readlane_b32 s16, v254, 3
	v_lshl_add_u64 v[4:5], s[0:1], 0, v[0:1]
	v_readlane_b32 s0, v254, 27
	v_readlane_b32 s30, v254, 17
	v_readlane_b32 s31, v254, 18
	v_readlane_b32 s1, v254, 28
	s_cselect_b64 s[6:7], -1, 0
	s_cmp_lg_u64 s[30:31], 0
	v_lshl_add_u64 v[6:7], s[0:1], 0, v[0:1]
	v_readlane_b32 s0, v254, 21
	s_cselect_b64 s[8:9], -1, 0
	s_mov_b32 s4, s0
	s_lshl_b32 s0, s0, 5
	v_readlane_b32 s17, v254, 4
	v_readlane_b32 s18, v254, 5
	v_readlane_b32 s19, v254, 6
	v_readlane_b32 s20, v254, 7
	v_readlane_b32 s21, v254, 8
	v_readlane_b32 s22, v254, 9
	v_readlane_b32 s23, v254, 10
	v_readlane_b32 s24, v254, 11
	v_readlane_b32 s25, v254, 12
	v_readlane_b32 s26, v254, 13
	v_readlane_b32 s27, v254, 14
	v_readlane_b32 s28, v254, 15
	v_readlane_b32 s29, v254, 16
	s_add_i32 s16, s0, 0xfffdae00
	s_lshl_b32 s0, s4, 1
	s_mov_b32 s5, 0
	v_mul_u32_u24_e32 v19, 0x84, v17
	v_or_b32_e32 v20, 2, v17
	v_or_b32_e32 v22, 4, v17
	v_or_b32_e32 v24, 6, v17
	v_or_b32_e32 v26, 8, v17
	v_or_b32_e32 v28, 10, v17
	v_or_b32_e32 v30, 12, v17
	v_or_b32_e32 v32, 14, v17
	v_or_b32_e32 v34, 16, v17
	v_or_b32_e32 v36, 18, v17
	v_or_b32_e32 v38, 20, v17
	v_or_b32_e32 v40, 22, v17
	v_or_b32_e32 v42, 24, v17
	v_or_b32_e32 v44, 26, v17
	v_or_b32_e32 v46, 28, v17
	v_or_b32_e32 v48, 30, v17
	v_or_b32_e32 v50, 32, v17
	v_or_b32_e32 v52, 34, v17
	v_or_b32_e32 v54, 36, v17
	v_or_b32_e32 v56, 38, v17
	v_or_b32_e32 v58, 40, v17
	v_or_b32_e32 v60, 42, v17
	v_or_b32_e32 v62, 44, v17
	v_or_b32_e32 v64, 46, v17
	v_or_b32_e32 v66, 48, v17
	v_or_b32_e32 v68, 50, v17
	v_or_b32_e32 v69, 52, v17
	v_or_b32_e32 v70, 54, v17
	v_or_b32_e32 v71, 56, v17
	v_or_b32_e32 v72, 58, v17
	v_or_b32_e32 v73, 60, v17
	v_or_b32_e32 v74, 62, v17
	v_lshl_add_u64 v[2:3], s[84:85], 0, v[0:1]
	v_or_b32_e32 v77, 8, v75
	v_or_b32_e32 v78, 16, v75
	v_or_b32_e32 v79, 24, v75
	v_bfe_u32 v80, v140, 3, 2
	v_lshl_add_u64 v[8:9], s[12:13], 0, v[0:1]
	v_lshl_add_u64 v[10:11], s[14:15], 0, v[0:1]
	v_lshl_add_u64 v[12:13], s[2:3], 0, v[0:1]
	s_lshl_b32 s17, s52, 5
	s_add_i32 s18, s0, 0xffffdae0
	s_lshl_b32 s19, s52, 1
	s_movk_i32 s20, 0x1fc8
	s_movk_i32 s21, 0x1fd8
	s_movk_i32 s22, 0x1fe8
	s_movk_i32 s23, 0x1ff8
	s_movk_i32 s24, 0xc00
	s_movk_i32 s25, 0x50
	s_movk_i32 s26, 0x300
	s_movk_i32 s27, 0x8a7
	s_movk_i32 s28, 0x22a0
	v_mov_b32_e32 v81, 0x2000
	v_mov_b32_e32 v82, 0xffffff61
	v_mov_b32_e32 v83, 0xffffff80
	s_mov_b32 s29, s4
	v_readlane_b32 s1, v254, 22
	s_branch .LBB0_39

.LBB0_226:
	s_cmp_eq_u32 s98, 0
	s_cbranch_scc1 .Lp01_to_barrier
	v_readlane_b32 s73, v254, 20
	s_cmp_eq_u32 s98, 1
	s_cbranch_scc1 .LBB0_281
	s_branch .Lp1_begin2

.Lp1_begin:
	v_readlane_b32 s0, v254, 19
	s_nop 3
	s_cmp_lt_u32 s0, 0x100
	s_cbranch_scc1 .Lp1_rows_first
	s_mov_b32 s98, 2
	s_branch .Lp01_items
.Lp1_rows_first:
	s_mov_b32 s98, 1
.Lp1_begin2:
	v_mbcnt_lo_u32_b32 v0, -1, 0
	v_mbcnt_hi_u32_b32 v0, -1, v0
	v_and_b32_e32 v0, 63, v0
	v_readlane_b32 s20, v254, 21
	v_readlane_b32 s16, v254, 3
	v_readlane_b32 s17, v254, 4
	v_readlane_b32 s26, v254, 13
	v_readlane_b32 s27, v254, 14
	s_ashr_i32 s53, s52, 31
	v_lshlrev_b32_e32 v1, 4, v0
	v_lshlrev_b32_e32 v2, 3, v0
	v_mov_b32_e32 v3, 0x358637bd
	s_nop 2
	global_load_dwordx4 v[10:13], v1, s[26:27]
	global_load_dwordx4 v[14:17], v1, s[26:27] offset:1024
	global_load_dwordx4 v[18:21], v1, s[26:27] offset:2048
	global_load_dwordx4 v[22:25], v1, s[26:27] offset:3072
	s_mov_b32 s21, s20
	s_lshl_b32 s0, s21, 12
	s_add_u32 s4, s16, s0
	s_addc_u32 s5, s17, 0
	s_ashr_i32 s0, s21, 12
	s_mul_i32 s0, s0, 0x6000
	s_add_u32 s6, s82, s0
	s_addc_u32 s7, s83, 0
	s_add_u32 s10, s6, 0x1000
	s_addc_u32 s11, s7, 0
	global_load_dwordx4 v[26:29], v1, s[4:5] nt
	global_load_dwordx4 v[30:33], v1, s[4:5] offset:1024 nt
	global_load_dwordx4 v[34:37], v1, s[4:5] offset:2048 nt
	global_load_dwordx4 v[38:41], v1, s[4:5] offset:3072 nt
	global_load_dwordx4 v[58:61], v1, s[6:7]
	global_load_dwordx4 v[62:65], v1, s[6:7] offset:1024
	global_load_dwordx4 v[66:69], v1, s[6:7] offset:2048
	global_load_dwordx4 v[70:73], v1, s[6:7] offset:3072
	global_load_dwordx4 v[74:77], v1, s[10:11]
	global_load_dwordx4 v[78:81], v1, s[10:11] offset:1024
	global_load_dwordx4 v[82:85], v1, s[10:11] offset:2048
	global_load_dwordx4 v[86:89], v1, s[10:11] offset:3072

.Lp1_done:
	s_cmp_eq_u32 s98, 1
	s_cbranch_scc0 .Lp1_fall
.Lp01_items:
	s_add_u32 s2, s82, 0x1000000
	s_addc_u32 s3, s83, 0
	s_add_u32 s14, s82, 0x1500000
	s_addc_u32 s15, s83, 0
	s_add_u32 s12, s82, 0x1600000
	s_addc_u32 s13, s83, 0
	s_mov_b32 s73, s99
	v_readlane_b32 s0, v254, 21
	s_nop 3
	s_cmpk_gt_i32 s0, 0x180f
	s_cbranch_scc1 .LBB0_226
	s_branch .Lp01_bb36
.Lp1_fall:
	s_mov_b32 s98, 3

	.amdhsa_kernel _Z14fwd_megakernel4Args
		.amdhsa_group_segment_fixed_size 0
		.amdhsa_private_segment_fixed_size 0
		.amdhsa_kernarg_size 448
		.amdhsa_user_sgpr_count 2
		.amdhsa_user_sgpr_dispatch_ptr 0
		.amdhsa_user_sgpr_queue_ptr 0
		.amdhsa_user_sgpr_kernarg_segment_ptr 1
		.amdhsa_user_sgpr_dispatch_id 0
		.amdhsa_user_sgpr_kernarg_preload_length 0
		.amdhsa_user_sgpr_kernarg_preload_offset 0
		.amdhsa_user_sgpr_private_segment_size 0
		.amdhsa_uses_dynamic_stack 0
		.amdhsa_enable_private_segment 0
		.amdhsa_system_sgpr_workgroup_id_x 1
		.amdhsa_system_sgpr_workgroup_id_y 0
		.amdhsa_system_sgpr_workgroup_id_z 0
		.amdhsa_system_sgpr_workgroup_info 0
		.amdhsa_system_vgpr_workitem_id 2
		.amdhsa_next_free_vgpr 256
		.amdhsa_next_free_sgpr 100
		.amdhsa_accum_offset 256
		.amdhsa_reserve_vcc 1
		.amdhsa_float_round_mode_32 0
		.amdhsa_float_round_mode_16_64 0
		.amdhsa_float_denorm_mode_32 3
		.amdhsa_float_denorm_mode_16_64 3
		.amdhsa_dx10_clamp 1
		.amdhsa_ieee_mode 1
		.amdhsa_fp16_overflow 0
		.amdhsa_tg_split 0
		.amdhsa_exception_fp_ieee_invalid_op 0
		.amdhsa_exception_fp_denorm_src 0
		.amdhsa_exception_fp_ieee_div_zero 0
		.amdhsa_exception_fp_ieee_overflow 0
		.amdhsa_exception_fp_ieee_underflow 0
		.amdhsa_exception_fp_ieee_inexact 0
		.amdhsa_exception_int_div_zero 0
	.end_amdhsa_kernel

amdhsa.kernels:
  - .agpr_count:     0
    .args:
      - .offset:         0
        .size:           192
        .value_kind:     by_value
      - .offset:         192
        .size:           4
        .value_kind:     hidden_block_count_x
      - .offset:         196
        .size:           4
        .value_kind:     hidden_block_count_y
      - .offset:         200
        .size:           4
        .value_kind:     hidden_block_count_z
      - .offset:         204
        .size:           2
        .value_kind:     hidden_group_size_x
      - .offset:         206
        .size:           2
        .value_kind:     hidden_group_size_y
      - .offset:         208
        .size:           2
        .value_kind:     hidden_group_size_z
      - .offset:         210
        .size:           2
        .value_kind:     hidden_remainder_x
      - .offset:         212
        .size:           2
        .value_kind:     hidden_remainder_y
      - .offset:         214
        .size:           2
        .value_kind:     hidden_remainder_z
      - .offset:         232
        .size:           8
        .value_kind:     hidden_global_offset_x
      - .offset:         240
        .size:           8
        .value_kind:     hidden_global_offset_y
      - .offset:         248
        .size:           8
        .value_kind:     hidden_global_offset_z
      - .offset:         256
        .size:           2
        .value_kind:     hidden_grid_dims
      - .offset:         280
        .size:           8
        .value_kind:     hidden_multigrid_sync_arg
      - .offset:         312
        .size:           4
        .value_kind:     hidden_dynamic_lds_size
    .group_segment_fixed_size: 0
    .kernarg_segment_align: 8
    .kernarg_segment_size: 448
    .language:       OpenCL C
    .language_version:
      - 2
      - 0
    .max_flat_workgroup_size: 512
    .name:           _Z14fwd_megakernel4Args
    .private_segment_fixed_size: 0
    .sgpr_count:     106
    .sgpr_spill_count: 135
    .symbol:         _Z14fwd_megakernel4Args.kd
    .uniform_work_group_size: 1
    .uses_dynamic_stack: false
    .vgpr_count:     256
    .vgpr_spill_count: 0
    .wavefront_size: 64
